# chain K-loop load segments: m0 writes hoisted above the two address adds that precede each LDS-DMA (they supply the wait state), the 12 pad s_nop removed
# speedup vs baseline: 1.0035x; 1.0035x over previous
.LBB0_391:
	ds_read_b128 v[148:151], v144
	ds_read_b128 v[152:155], v144 offset:1024
	ds_read_b128 v[156:159], v144 offset:2048
	ds_read_b128 v[160:163], v144 offset:3072
	ds_read_b128 v[174:177], v145
	ds_read_b128 v[178:181], v145 offset:1024
	ds_read_b128 v[182:185], v145 offset:2048
	ds_read_b128 v[186:189], v145 offset:3072
	v_lshl_add_u64 v[236:237], v[142:143], 0, s[62:63]
	s_mov_b32 m0, s55
	v_lshl_add_u64 v[238:239], v[236:237], 0, s[44:45]
	ds_read_b128 v[190:193], v195
	ds_read_b128 v[208:211], v195 offset:1024
	ds_read_b128 v[212:215], v195 offset:2048
	ds_read_b128 v[216:219], v195 offset:3072
	ds_read_b128 v[220:223], v195 offset:4096
	ds_read_b128 v[224:227], v195 offset:5120
	ds_read_b128 v[228:231], v195 offset:6144
	ds_read_b128 v[232:235], v195 offset:7168
	global_load_lds_dwordx4 v[238:239], off
	s_mov_b32 m0, s97
	v_lshl_add_u64 v[238:239], v[140:141], 0, s[62:63]
	v_lshl_add_u64 v[240:241], v[238:239], 0, s[44:45]
	global_load_lds_dwordx4 v[240:241], off
	s_waitcnt vmcnt(8)
	s_waitcnt lgkmcnt(0)
	s_barrier
	s_setprio 1
	s_waitcnt lgkmcnt(0)
	v_mfma_f32_16x16x32_bf16 v[124:127], v[148:151], v[190:193], v[124:127]
	v_mfma_f32_16x16x32_bf16 v[120:123], v[156:159], v[190:193], v[120:123]
	v_mfma_f32_16x16x32_bf16 v[116:119], v[148:151], v[212:215], v[116:119]
	v_mfma_f32_16x16x32_bf16 v[112:115], v[156:159], v[212:215], v[112:115]
	v_mfma_f32_16x16x32_bf16 v[108:111], v[148:151], v[220:223], v[108:111]
	v_mfma_f32_16x16x32_bf16 v[104:107], v[156:159], v[220:223], v[104:107]
	v_mfma_f32_16x16x32_bf16 v[100:103], v[148:151], v[228:231], v[100:103]
	v_mfma_f32_16x16x32_bf16 v[96:99], v[156:159], v[228:231], v[96:99]
	v_mfma_f32_16x16x32_bf16 v[124:127], v[152:155], v[208:211], v[124:127]
	v_mfma_f32_16x16x32_bf16 v[120:123], v[160:163], v[208:211], v[120:123]
	v_mfma_f32_16x16x32_bf16 v[116:119], v[152:155], v[216:219], v[116:119]
	v_mfma_f32_16x16x32_bf16 v[112:115], v[160:163], v[216:219], v[112:115]
	v_mfma_f32_16x16x32_bf16 v[108:111], v[152:155], v[224:227], v[108:111]
	v_mfma_f32_16x16x32_bf16 v[104:107], v[160:163], v[224:227], v[104:107]
	v_mfma_f32_16x16x32_bf16 v[100:103], v[152:155], v[232:235], v[100:103]
	v_mfma_f32_16x16x32_bf16 v[96:99], v[160:163], v[232:235], v[96:99]
	s_setprio 0
	s_setprio 1
	v_mfma_f32_16x16x32_bf16 v[92:95], v[174:177], v[190:193], v[92:95]
	v_mfma_f32_16x16x32_bf16 v[88:91], v[182:185], v[190:193], v[88:91]
	v_mfma_f32_16x16x32_bf16 v[84:87], v[174:177], v[212:215], v[84:87]
	v_mfma_f32_16x16x32_bf16 v[80:83], v[182:185], v[212:215], v[80:83]
	v_mfma_f32_16x16x32_bf16 v[76:79], v[174:177], v[220:223], v[76:79]
	v_mfma_f32_16x16x32_bf16 v[72:75], v[182:185], v[220:223], v[72:75]
	v_mfma_f32_16x16x32_bf16 v[68:71], v[174:177], v[228:231], v[68:71]
	v_mfma_f32_16x16x32_bf16 v[64:67], v[182:185], v[228:231], v[64:67]
	v_mfma_f32_16x16x32_bf16 v[92:95], v[178:181], v[208:211], v[92:95]
	v_mfma_f32_16x16x32_bf16 v[88:91], v[186:189], v[208:211], v[88:91]
	v_mfma_f32_16x16x32_bf16 v[84:87], v[178:181], v[216:219], v[84:87]
	v_mfma_f32_16x16x32_bf16 v[80:83], v[186:189], v[216:219], v[80:83]
	v_mfma_f32_16x16x32_bf16 v[76:79], v[178:181], v[224:227], v[76:79]
	v_mfma_f32_16x16x32_bf16 v[72:75], v[186:189], v[224:227], v[72:75]
	v_mfma_f32_16x16x32_bf16 v[68:71], v[178:181], v[232:235], v[68:71]
	v_mfma_f32_16x16x32_bf16 v[64:67], v[186:189], v[232:235], v[64:67]
	s_setprio 0
	s_barrier
	v_lshl_add_u64 v[240:241], v[128:129], 0, s[62:63]
	s_mov_b32 m0, s2
	v_lshl_add_u64 v[242:243], v[240:241], 0, s[46:47]
	ds_read_b128 v[190:193], v195 offset:16384
	ds_read_b128 v[208:211], v195 offset:17408
	ds_read_b128 v[212:215], v195 offset:18432
	ds_read_b128 v[216:219], v195 offset:19456
	ds_read_b128 v[220:223], v195 offset:20480
	ds_read_b128 v[224:227], v195 offset:21504
	ds_read_b128 v[228:231], v195 offset:22528
	ds_read_b128 v[232:235], v195 offset:23552
	global_load_lds_dwordx4 v[242:243], off
	s_mov_b32 m0, s16
	v_lshl_add_u64 v[242:243], v[130:131], 0, s[62:63]
	v_lshl_add_u64 v[244:245], v[242:243], 0, s[46:47]
	global_load_lds_dwordx4 v[244:245], off
	s_mov_b32 m0, s17
	v_lshl_add_u64 v[244:245], v[138:139], 0, s[62:63]
	v_lshl_add_u64 v[246:247], v[244:245], 0, s[46:47]
	global_load_lds_dwordx4 v[246:247], off
	s_mov_b32 m0, s14
	v_lshl_add_u64 v[246:247], v[136:137], 0, s[62:63]
	v_lshl_add_u64 v[248:249], v[246:247], 0, s[46:47]
	global_load_lds_dwordx4 v[248:249], off
	s_mov_b32 m0, s89
	v_lshl_add_u64 v[248:249], v[132:133], 0, s[62:63]
	v_lshl_add_u64 v[250:251], v[248:249], 0, s[46:47]
	global_load_lds_dwordx4 v[250:251], off
	s_mov_b32 m0, s90
	v_lshl_add_u64 v[250:251], v[134:135], 0, s[62:63]
	v_lshl_add_u64 v[166:167], v[250:251], 0, s[46:47]
	global_load_lds_dwordx4 v[166:167], off
	s_waitcnt vmcnt(8)
	s_waitcnt lgkmcnt(0)
	s_barrier
	s_setprio 1
	s_waitcnt lgkmcnt(0)
	v_mfma_f32_16x16x32_bf16 v[60:63], v[148:151], v[190:193], v[60:63]
	v_mfma_f32_16x16x32_bf16 v[56:59], v[156:159], v[190:193], v[56:59]
	v_mfma_f32_16x16x32_bf16 v[52:55], v[148:151], v[212:215], v[52:55]
	v_mfma_f32_16x16x32_bf16 v[48:51], v[156:159], v[212:215], v[48:51]
	v_mfma_f32_16x16x32_bf16 v[44:47], v[148:151], v[220:223], v[44:47]
	v_mfma_f32_16x16x32_bf16 v[40:43], v[156:159], v[220:223], v[40:43]
	v_mfma_f32_16x16x32_bf16 v[36:39], v[148:151], v[228:231], v[36:39]
	v_mfma_f32_16x16x32_bf16 v[32:35], v[156:159], v[228:231], v[32:35]
	v_mfma_f32_16x16x32_bf16 v[60:63], v[152:155], v[208:211], v[60:63]
	v_mfma_f32_16x16x32_bf16 v[56:59], v[160:163], v[208:211], v[56:59]
	v_mfma_f32_16x16x32_bf16 v[52:55], v[152:155], v[216:219], v[52:55]
	v_mfma_f32_16x16x32_bf16 v[48:51], v[160:163], v[216:219], v[48:51]
	v_mfma_f32_16x16x32_bf16 v[44:47], v[152:155], v[224:227], v[44:47]
	v_mfma_f32_16x16x32_bf16 v[40:43], v[160:163], v[224:227], v[40:43]
	v_mfma_f32_16x16x32_bf16 v[36:39], v[152:155], v[232:235], v[36:39]
	v_mfma_f32_16x16x32_bf16 v[32:35], v[160:163], v[232:235], v[32:35]
	s_setprio 0
	s_setprio 1
	v_mfma_f32_16x16x32_bf16 v[28:31], v[174:177], v[190:193], v[28:31]
	v_mfma_f32_16x16x32_bf16 v[24:27], v[182:185], v[190:193], v[24:27]
	v_mfma_f32_16x16x32_bf16 v[20:23], v[174:177], v[212:215], v[20:23]
	v_mfma_f32_16x16x32_bf16 v[16:19], v[182:185], v[212:215], v[16:19]
	v_mfma_f32_16x16x32_bf16 v[12:15], v[174:177], v[220:223], v[12:15]
	v_mfma_f32_16x16x32_bf16 v[8:11], v[182:185], v[220:223], v[8:11]
	v_mfma_f32_16x16x32_bf16 v[4:7], v[174:177], v[228:231], v[4:7]
	v_mfma_f32_16x16x32_bf16 v[0:3], v[182:185], v[228:231], v[0:3]
	v_mfma_f32_16x16x32_bf16 v[28:31], v[178:181], v[208:211], v[28:31]
	v_mfma_f32_16x16x32_bf16 v[24:27], v[186:189], v[208:211], v[24:27]
	v_mfma_f32_16x16x32_bf16 v[20:23], v[178:181], v[216:219], v[20:23]
	v_mfma_f32_16x16x32_bf16 v[16:19], v[186:189], v[216:219], v[16:19]
	v_mfma_f32_16x16x32_bf16 v[12:15], v[178:181], v[224:227], v[12:15]
	v_mfma_f32_16x16x32_bf16 v[8:11], v[186:189], v[224:227], v[8:11]
	v_mfma_f32_16x16x32_bf16 v[4:7], v[178:181], v[232:235], v[4:7]
	v_mfma_f32_16x16x32_bf16 v[0:3], v[186:189], v[232:235], v[0:3]
	s_setprio 0
	s_barrier
	ds_read_b128 v[148:151], v146
	ds_read_b128 v[152:155], v146 offset:1024
	ds_read_b128 v[156:159], v146 offset:2048
	ds_read_b128 v[160:163], v146 offset:3072
	ds_read_b128 v[174:177], v147
	ds_read_b128 v[178:181], v147 offset:1024
	ds_read_b128 v[182:185], v147 offset:2048
	ds_read_b128 v[186:189], v147 offset:3072
	s_mov_b32 m0, s91
	v_lshl_add_u64 v[166:167], v[236:237], 0, s[46:47]
	ds_read_b128 v[190:193], v195 offset:32768
	ds_read_b128 v[208:211], v195 offset:33792
	ds_read_b128 v[212:215], v195 offset:34816
	ds_read_b128 v[216:219], v195 offset:35840
	ds_read_b128 v[220:223], v195 offset:36864
	ds_read_b128 v[224:227], v195 offset:37888
	ds_read_b128 v[228:231], v195 offset:38912
	ds_read_b128 v[232:235], v195 offset:39936
	global_load_lds_dwordx4 v[166:167], off
	v_lshl_add_u64 v[166:167], v[238:239], 0, s[46:47]
	s_mov_b32 m0, s92
	s_nop 0
	global_load_lds_dwordx4 v[166:167], off
	s_waitcnt vmcnt(8)
	s_waitcnt lgkmcnt(0)
	s_barrier
	s_setprio 1
	s_waitcnt lgkmcnt(0)
	v_mfma_f32_16x16x32_bf16 v[124:127], v[148:151], v[190:193], v[124:127]
	v_mfma_f32_16x16x32_bf16 v[120:123], v[156:159], v[190:193], v[120:123]
	v_mfma_f32_16x16x32_bf16 v[116:119], v[148:151], v[212:215], v[116:119]
	v_mfma_f32_16x16x32_bf16 v[112:115], v[156:159], v[212:215], v[112:115]
	v_mfma_f32_16x16x32_bf16 v[108:111], v[148:151], v[220:223], v[108:111]
	v_mfma_f32_16x16x32_bf16 v[104:107], v[156:159], v[220:223], v[104:107]
	v_mfma_f32_16x16x32_bf16 v[100:103], v[148:151], v[228:231], v[100:103]
	v_mfma_f32_16x16x32_bf16 v[96:99], v[156:159], v[228:231], v[96:99]
	v_mfma_f32_16x16x32_bf16 v[124:127], v[152:155], v[208:211], v[124:127]
	v_mfma_f32_16x16x32_bf16 v[120:123], v[160:163], v[208:211], v[120:123]
	v_mfma_f32_16x16x32_bf16 v[116:119], v[152:155], v[216:219], v[116:119]
	v_mfma_f32_16x16x32_bf16 v[112:115], v[160:163], v[216:219], v[112:115]
	v_mfma_f32_16x16x32_bf16 v[108:111], v[152:155], v[224:227], v[108:111]
	v_mfma_f32_16x16x32_bf16 v[104:107], v[160:163], v[224:227], v[104:107]
	v_mfma_f32_16x16x32_bf16 v[100:103], v[152:155], v[232:235], v[100:103]
	v_mfma_f32_16x16x32_bf16 v[96:99], v[160:163], v[232:235], v[96:99]
	s_setprio 0
	s_setprio 1
	v_mfma_f32_16x16x32_bf16 v[92:95], v[174:177], v[190:193], v[92:95]
	v_mfma_f32_16x16x32_bf16 v[88:91], v[182:185], v[190:193], v[88:91]
	v_mfma_f32_16x16x32_bf16 v[84:87], v[174:177], v[212:215], v[84:87]
	v_mfma_f32_16x16x32_bf16 v[80:83], v[182:185], v[212:215], v[80:83]
	v_mfma_f32_16x16x32_bf16 v[76:79], v[174:177], v[220:223], v[76:79]
	v_mfma_f32_16x16x32_bf16 v[72:75], v[182:185], v[220:223], v[72:75]
	v_mfma_f32_16x16x32_bf16 v[68:71], v[174:177], v[228:231], v[68:71]
	v_mfma_f32_16x16x32_bf16 v[64:67], v[182:185], v[228:231], v[64:67]
	v_mfma_f32_16x16x32_bf16 v[92:95], v[178:181], v[208:211], v[92:95]
	v_mfma_f32_16x16x32_bf16 v[88:91], v[186:189], v[208:211], v[88:91]
	v_mfma_f32_16x16x32_bf16 v[84:87], v[178:181], v[216:219], v[84:87]
	v_mfma_f32_16x16x32_bf16 v[80:83], v[186:189], v[216:219], v[80:83]
	v_mfma_f32_16x16x32_bf16 v[76:79], v[178:181], v[224:227], v[76:79]
	v_mfma_f32_16x16x32_bf16 v[72:75], v[186:189], v[224:227], v[72:75]
	v_mfma_f32_16x16x32_bf16 v[68:71], v[178:181], v[232:235], v[68:71]
	v_mfma_f32_16x16x32_bf16 v[64:67], v[186:189], v[232:235], v[64:67]
	s_setprio 0
	s_barrier
	s_mov_b32 m0, s15
	v_lshl_add_u64 v[166:167], v[240:241], 0, s[48:49]
	ds_read_b128 v[190:193], v195 offset:49152
	ds_read_b128 v[208:211], v195 offset:50176
	ds_read_b128 v[212:215], v195 offset:51200
	ds_read_b128 v[216:219], v195 offset:52224
	ds_read_b128 v[220:223], v195 offset:53248
	ds_read_b128 v[224:227], v195 offset:54272
	ds_read_b128 v[228:231], v195 offset:55296
	ds_read_b128 v[232:235], v195 offset:56320
	global_load_lds_dwordx4 v[166:167], off
	v_lshl_add_u64 v[166:167], v[242:243], 0, s[48:49]
	s_mov_b32 m0, s33
	s_nop 0
	global_load_lds_dwordx4 v[166:167], off
	v_lshl_add_u64 v[166:167], v[244:245], 0, s[48:49]
	s_mov_b32 m0, s3
	s_nop 0
	global_load_lds_dwordx4 v[166:167], off
	v_lshl_add_u64 v[166:167], v[246:247], 0, s[48:49]
	s_mov_b32 m0, s20
	s_nop 0
	global_load_lds_dwordx4 v[166:167], off
	v_lshl_add_u64 v[166:167], v[248:249], 0, s[48:49]
	s_mov_b32 m0, s93
	s_nop 0
	global_load_lds_dwordx4 v[166:167], off
	v_lshl_add_u64 v[166:167], v[250:251], 0, s[48:49]
	s_mov_b32 m0, s94
	s_nop 0
	global_load_lds_dwordx4 v[166:167], off
	s_waitcnt vmcnt(8)
	s_waitcnt lgkmcnt(0)
	s_barrier
	s_setprio 1
	s_waitcnt lgkmcnt(0)
	v_mfma_f32_16x16x32_bf16 v[60:63], v[148:151], v[190:193], v[60:63]
	v_mfma_f32_16x16x32_bf16 v[56:59], v[156:159], v[190:193], v[56:59]
	v_mfma_f32_16x16x32_bf16 v[52:55], v[148:151], v[212:215], v[52:55]
	v_mfma_f32_16x16x32_bf16 v[48:51], v[156:159], v[212:215], v[48:51]
	v_mfma_f32_16x16x32_bf16 v[44:47], v[148:151], v[220:223], v[44:47]
	v_mfma_f32_16x16x32_bf16 v[40:43], v[156:159], v[220:223], v[40:43]
	v_mfma_f32_16x16x32_bf16 v[36:39], v[148:151], v[228:231], v[36:39]
	v_mfma_f32_16x16x32_bf16 v[32:35], v[156:159], v[228:231], v[32:35]
	v_mfma_f32_16x16x32_bf16 v[60:63], v[152:155], v[208:211], v[60:63]
	v_mfma_f32_16x16x32_bf16 v[56:59], v[160:163], v[208:211], v[56:59]
	v_mfma_f32_16x16x32_bf16 v[52:55], v[152:155], v[216:219], v[52:55]
	v_mfma_f32_16x16x32_bf16 v[48:51], v[160:163], v[216:219], v[48:51]
	v_mfma_f32_16x16x32_bf16 v[44:47], v[152:155], v[224:227], v[44:47]
	v_mfma_f32_16x16x32_bf16 v[40:43], v[160:163], v[224:227], v[40:43]
	v_mfma_f32_16x16x32_bf16 v[36:39], v[152:155], v[232:235], v[36:39]
	v_mfma_f32_16x16x32_bf16 v[32:35], v[160:163], v[232:235], v[32:35]
	s_setprio 0
	s_setprio 1
	v_mfma_f32_16x16x32_bf16 v[28:31], v[174:177], v[190:193], v[28:31]
	v_mfma_f32_16x16x32_bf16 v[24:27], v[182:185], v[190:193], v[24:27]
	v_mfma_f32_16x16x32_bf16 v[20:23], v[174:177], v[212:215], v[20:23]
	s_add_u32 s62, s62, 0x100
	v_mfma_f32_16x16x32_bf16 v[16:19], v[182:185], v[212:215], v[16:19]
	s_addc_u32 s63, s63, 0
	v_mfma_f32_16x16x32_bf16 v[12:15], v[174:177], v[220:223], v[12:15]
	s_add_i32 s32, s22, 2
	v_mfma_f32_16x16x32_bf16 v[8:11], v[182:185], v[220:223], v[8:11]
	s_add_i32 s99, s22, -4
	v_mfma_f32_16x16x32_bf16 v[4:7], v[174:177], v[228:231], v[4:7]
	s_cmp_ge_i32 s99, s29
	v_mfma_f32_16x16x32_bf16 v[0:3], v[182:185], v[228:231], v[0:3]
	s_cselect_b32 s98, 0, 1
	v_mfma_f32_16x16x32_bf16 v[28:31], v[178:181], v[208:211], v[28:31]
	s_cmp_eq_u32 s34, s32
	v_mfma_f32_16x16x32_bf16 v[24:27], v[186:189], v[208:211], v[24:27]
	s_cselect_b64 vcc, -1, 0
	v_mfma_f32_16x16x32_bf16 v[20:23], v[178:181], v[216:219], v[20:23]
	s_and_b64 vcc, s[66:67], vcc
	v_mfma_f32_16x16x32_bf16 v[16:19], v[186:189], v[216:219], v[16:19]
	s_cselect_b32 s98, 0, s98
	v_mfma_f32_16x16x32_bf16 v[12:15], v[178:181], v[224:227], v[12:15]
	s_and_b64 vcc, exec, s[8:9]
	v_mfma_f32_16x16x32_bf16 v[8:11], v[186:189], v[224:227], v[8:11]
	s_cselect_b32 s98, s98, 0
	v_mfma_f32_16x16x32_bf16 v[4:7], v[178:181], v[232:235], v[4:7]
	s_cmp_lg_u32 s98, 0
	v_mfma_f32_16x16x32_bf16 v[0:3], v[186:189], v[232:235], v[0:3]
	s_setprio 0
	s_barrier
	s_cbranch_scc1 .Lk_fastb
	s_and_b64 vcc, exec, s[8:9]
	s_cbranch_vccnz .LBB0_394
	s_waitcnt vmcnt(16)
	v_mov_b32_e32 v148, s82
	v_mov_b32_e32 v149, s21
	ds_read_b32 v148, v148
	ds_read_b32 v149, v149 offset:60
	s_mov_b64 s[64:65], 0
	s_waitcnt lgkmcnt(0)
	v_readfirstlane_b32 s8, v148
	v_readfirstlane_b32 s9, v149
	s_mul_i32 s9, s9, s28
	s_cmp_lt_u32 s8, s9
	s_cbranch_scc1 .LBB0_394
	buffer_inv sc1
	s_mov_b64 s[64:65], -1

.LBB0_2163:
	ds_read_b128 v[150:153], v146
	ds_read_b128 v[154:157], v146 offset:1024
	ds_read_b128 v[158:161], v146 offset:2048
	ds_read_b128 v[162:165], v146 offset:3072
	ds_read_b128 v[166:169], v147
	ds_read_b128 v[180:183], v147 offset:1024
	ds_read_b128 v[184:187], v147 offset:2048
	ds_read_b128 v[188:191], v147 offset:3072
	v_lshl_add_u64 v[242:243], v[144:145], 0, s[38:39]
	s_mov_b32 m0, s95
	v_lshl_add_u64 v[244:245], v[242:243], 0, s[78:79]
	ds_read_b128 v[192:195], v200
	ds_read_b128 v[196:199], v200 offset:1024
	ds_read_b128 v[218:221], v200 offset:2048
	ds_read_b128 v[222:225], v200 offset:3072
	ds_read_b128 v[226:229], v200 offset:4096
	ds_read_b128 v[230:233], v200 offset:5120
	ds_read_b128 v[234:237], v200 offset:6144
	ds_read_b128 v[238:241], v200 offset:7168
	global_load_lds_dwordx4 v[244:245], off
	s_mov_b32 m0, s96
	v_lshl_add_u64 v[244:245], v[142:143], 0, s[38:39]
	v_lshl_add_u64 v[246:247], v[244:245], 0, s[78:79]
	global_load_lds_dwordx4 v[246:247], off
	s_waitcnt vmcnt(8)
	s_waitcnt lgkmcnt(0)
	s_barrier
	s_setprio 1
	s_waitcnt lgkmcnt(0)
	v_mfma_f32_16x16x32_bf16 v[126:129], v[150:153], v[192:195], v[126:129]
	v_mfma_f32_16x16x32_bf16 v[122:125], v[158:161], v[192:195], v[122:125]
	v_mfma_f32_16x16x32_bf16 v[118:121], v[150:153], v[218:221], v[118:121]
	v_mfma_f32_16x16x32_bf16 v[114:117], v[158:161], v[218:221], v[114:117]
	v_mfma_f32_16x16x32_bf16 v[110:113], v[150:153], v[226:229], v[110:113]
	v_mfma_f32_16x16x32_bf16 v[106:109], v[158:161], v[226:229], v[106:109]
	v_mfma_f32_16x16x32_bf16 v[102:105], v[150:153], v[234:237], v[102:105]
	v_mfma_f32_16x16x32_bf16 v[98:101], v[158:161], v[234:237], v[98:101]
	v_mfma_f32_16x16x32_bf16 v[126:129], v[154:157], v[196:199], v[126:129]
	v_mfma_f32_16x16x32_bf16 v[122:125], v[162:165], v[196:199], v[122:125]
	v_mfma_f32_16x16x32_bf16 v[118:121], v[154:157], v[222:225], v[118:121]
	v_mfma_f32_16x16x32_bf16 v[114:117], v[162:165], v[222:225], v[114:117]
	v_mfma_f32_16x16x32_bf16 v[110:113], v[154:157], v[230:233], v[110:113]
	v_mfma_f32_16x16x32_bf16 v[106:109], v[162:165], v[230:233], v[106:109]
	v_mfma_f32_16x16x32_bf16 v[102:105], v[154:157], v[238:241], v[102:105]
	v_mfma_f32_16x16x32_bf16 v[98:101], v[162:165], v[238:241], v[98:101]
	s_setprio 0
	s_setprio 1
	v_mfma_f32_16x16x32_bf16 v[94:97], v[166:169], v[192:195], v[94:97]
	v_mfma_f32_16x16x32_bf16 v[90:93], v[184:187], v[192:195], v[90:93]
	v_mfma_f32_16x16x32_bf16 v[86:89], v[166:169], v[218:221], v[86:89]
	v_mfma_f32_16x16x32_bf16 v[82:85], v[184:187], v[218:221], v[82:85]
	v_mfma_f32_16x16x32_bf16 v[78:81], v[166:169], v[226:229], v[78:81]
	v_mfma_f32_16x16x32_bf16 v[74:77], v[184:187], v[226:229], v[74:77]
	v_mfma_f32_16x16x32_bf16 v[70:73], v[166:169], v[234:237], v[70:73]
	v_mfma_f32_16x16x32_bf16 v[66:69], v[184:187], v[234:237], v[66:69]
	v_mfma_f32_16x16x32_bf16 v[94:97], v[180:183], v[196:199], v[94:97]
	v_mfma_f32_16x16x32_bf16 v[90:93], v[188:191], v[196:199], v[90:93]
	v_mfma_f32_16x16x32_bf16 v[86:89], v[180:183], v[222:225], v[86:89]
	v_mfma_f32_16x16x32_bf16 v[82:85], v[188:191], v[222:225], v[82:85]
	v_mfma_f32_16x16x32_bf16 v[78:81], v[180:183], v[230:233], v[78:81]
	v_mfma_f32_16x16x32_bf16 v[74:77], v[188:191], v[230:233], v[74:77]
	v_mfma_f32_16x16x32_bf16 v[70:73], v[180:183], v[238:241], v[70:73]
	v_mfma_f32_16x16x32_bf16 v[66:69], v[188:191], v[238:241], v[66:69]
	s_setprio 0
	s_barrier
	v_lshl_add_u64 v[246:247], v[130:131], 0, s[38:39]
	s_mov_b32 m0, s2
	v_lshl_add_u64 v[248:249], v[246:247], 0, s[76:77]
	ds_read_b128 v[192:195], v200 offset:16384
	ds_read_b128 v[196:199], v200 offset:17408
	ds_read_b128 v[218:221], v200 offset:18432
	ds_read_b128 v[222:225], v200 offset:19456
	ds_read_b128 v[226:229], v200 offset:20480
	ds_read_b128 v[230:233], v200 offset:21504
	ds_read_b128 v[234:237], v200 offset:22528
	ds_read_b128 v[238:241], v200 offset:23552
	global_load_lds_dwordx4 v[248:249], off
	s_mov_b32 m0, s56
	v_lshl_add_u64 v[248:249], v[132:133], 0, s[38:39]
	v_lshl_add_u64 v[250:251], v[248:249], 0, s[76:77]
	global_load_lds_dwordx4 v[250:251], off
	s_mov_b32 m0, s19
	v_lshl_add_u64 v[250:251], v[140:141], 0, s[38:39]
	v_lshl_add_u64 v[206:207], v[250:251], 0, s[76:77]
	global_load_lds_dwordx4 v[206:207], off
	s_mov_b32 m0, s63
	v_lshl_add_u64 v[206:207], v[138:139], 0, s[38:39]
	v_lshl_add_u64 v[204:205], v[206:207], 0, s[76:77]
	global_load_lds_dwordx4 v[204:205], off
	s_mov_b32 m0, s53
	v_lshl_add_u64 v[204:205], v[134:135], 0, s[38:39]
	v_lshl_add_u64 v[170:171], v[204:205], 0, s[76:77]
	global_load_lds_dwordx4 v[170:171], off
	s_mov_b32 m0, s92
	v_lshl_add_u64 v[170:171], v[136:137], 0, s[38:39]
	v_lshl_add_u64 v[208:209], v[170:171], 0, s[76:77]
	global_load_lds_dwordx4 v[208:209], off
	s_waitcnt vmcnt(8)
	s_waitcnt lgkmcnt(0)
	s_barrier
	s_setprio 1
	s_waitcnt lgkmcnt(0)
	v_mfma_f32_16x16x32_bf16 v[62:65], v[150:153], v[192:195], v[62:65]
	v_mfma_f32_16x16x32_bf16 v[58:61], v[158:161], v[192:195], v[58:61]
	v_mfma_f32_16x16x32_bf16 v[54:57], v[150:153], v[218:221], v[54:57]
	v_mfma_f32_16x16x32_bf16 v[50:53], v[158:161], v[218:221], v[50:53]
	v_mfma_f32_16x16x32_bf16 v[46:49], v[150:153], v[226:229], v[46:49]
	v_mfma_f32_16x16x32_bf16 v[42:45], v[158:161], v[226:229], v[42:45]
	v_mfma_f32_16x16x32_bf16 v[38:41], v[150:153], v[234:237], v[38:41]
	v_mfma_f32_16x16x32_bf16 v[34:37], v[158:161], v[234:237], v[34:37]
	v_mfma_f32_16x16x32_bf16 v[62:65], v[154:157], v[196:199], v[62:65]
	v_mfma_f32_16x16x32_bf16 v[58:61], v[162:165], v[196:199], v[58:61]
	v_mfma_f32_16x16x32_bf16 v[54:57], v[154:157], v[222:225], v[54:57]
	v_mfma_f32_16x16x32_bf16 v[50:53], v[162:165], v[222:225], v[50:53]
	v_mfma_f32_16x16x32_bf16 v[46:49], v[154:157], v[230:233], v[46:49]
	v_mfma_f32_16x16x32_bf16 v[42:45], v[162:165], v[230:233], v[42:45]
	v_mfma_f32_16x16x32_bf16 v[38:41], v[154:157], v[238:241], v[38:41]
	v_mfma_f32_16x16x32_bf16 v[34:37], v[162:165], v[238:241], v[34:37]
	s_setprio 0
	s_setprio 1
	v_mfma_f32_16x16x32_bf16 v[30:33], v[166:169], v[192:195], v[30:33]
	v_mfma_f32_16x16x32_bf16 v[26:29], v[184:187], v[192:195], v[26:29]
	v_mfma_f32_16x16x32_bf16 v[22:25], v[166:169], v[218:221], v[22:25]
	v_mfma_f32_16x16x32_bf16 v[18:21], v[184:187], v[218:221], v[18:21]
	v_mfma_f32_16x16x32_bf16 v[14:17], v[166:169], v[226:229], v[14:17]
	v_mfma_f32_16x16x32_bf16 v[10:13], v[184:187], v[226:229], v[10:13]
	v_mfma_f32_16x16x32_bf16 v[6:9], v[166:169], v[234:237], v[6:9]
	v_mfma_f32_16x16x32_bf16 v[2:5], v[184:187], v[234:237], v[2:5]
	v_mfma_f32_16x16x32_bf16 v[30:33], v[180:183], v[196:199], v[30:33]
	v_mfma_f32_16x16x32_bf16 v[26:29], v[188:191], v[196:199], v[26:29]
	v_mfma_f32_16x16x32_bf16 v[22:25], v[180:183], v[222:225], v[22:25]
	v_mfma_f32_16x16x32_bf16 v[18:21], v[188:191], v[222:225], v[18:21]
	v_mfma_f32_16x16x32_bf16 v[14:17], v[180:183], v[230:233], v[14:17]
	v_mfma_f32_16x16x32_bf16 v[10:13], v[188:191], v[230:233], v[10:13]
	v_mfma_f32_16x16x32_bf16 v[6:9], v[180:183], v[238:241], v[6:9]
	v_mfma_f32_16x16x32_bf16 v[2:5], v[188:191], v[238:241], v[2:5]
	s_setprio 0
	s_barrier
	ds_read_b128 v[150:153], v148
	ds_read_b128 v[154:157], v148 offset:1024
	ds_read_b128 v[158:161], v148 offset:2048
	ds_read_b128 v[162:165], v148 offset:3072
	ds_read_b128 v[166:169], v149
	ds_read_b128 v[180:183], v149 offset:1024
	ds_read_b128 v[184:187], v149 offset:2048
	ds_read_b128 v[188:191], v149 offset:3072
	s_mov_b32 m0, s93
	v_lshl_add_u64 v[208:209], v[242:243], 0, s[76:77]
	ds_read_b128 v[192:195], v200 offset:32768
	ds_read_b128 v[196:199], v200 offset:33792
	ds_read_b128 v[218:221], v200 offset:34816
	ds_read_b128 v[222:225], v200 offset:35840
	ds_read_b128 v[226:229], v200 offset:36864
	ds_read_b128 v[230:233], v200 offset:37888
	ds_read_b128 v[234:237], v200 offset:38912
	ds_read_b128 v[238:241], v200 offset:39936
	global_load_lds_dwordx4 v[208:209], off
	v_lshl_add_u64 v[208:209], v[244:245], 0, s[76:77]
	s_mov_b32 m0, s54
	s_nop 0
	global_load_lds_dwordx4 v[208:209], off
	s_waitcnt vmcnt(8)
	s_waitcnt lgkmcnt(0)
	s_barrier
	s_setprio 1
	s_waitcnt lgkmcnt(0)
	v_mfma_f32_16x16x32_bf16 v[126:129], v[150:153], v[192:195], v[126:129]
	v_mfma_f32_16x16x32_bf16 v[122:125], v[158:161], v[192:195], v[122:125]
	v_mfma_f32_16x16x32_bf16 v[118:121], v[150:153], v[218:221], v[118:121]
	v_mfma_f32_16x16x32_bf16 v[114:117], v[158:161], v[218:221], v[114:117]
	v_mfma_f32_16x16x32_bf16 v[110:113], v[150:153], v[226:229], v[110:113]
	v_mfma_f32_16x16x32_bf16 v[106:109], v[158:161], v[226:229], v[106:109]
	v_mfma_f32_16x16x32_bf16 v[102:105], v[150:153], v[234:237], v[102:105]
	v_mfma_f32_16x16x32_bf16 v[98:101], v[158:161], v[234:237], v[98:101]
	v_mfma_f32_16x16x32_bf16 v[126:129], v[154:157], v[196:199], v[126:129]
	v_mfma_f32_16x16x32_bf16 v[122:125], v[162:165], v[196:199], v[122:125]
	v_mfma_f32_16x16x32_bf16 v[118:121], v[154:157], v[222:225], v[118:121]
	v_mfma_f32_16x16x32_bf16 v[114:117], v[162:165], v[222:225], v[114:117]
	v_mfma_f32_16x16x32_bf16 v[110:113], v[154:157], v[230:233], v[110:113]
	v_mfma_f32_16x16x32_bf16 v[106:109], v[162:165], v[230:233], v[106:109]
	v_mfma_f32_16x16x32_bf16 v[102:105], v[154:157], v[238:241], v[102:105]
	v_mfma_f32_16x16x32_bf16 v[98:101], v[162:165], v[238:241], v[98:101]
	s_setprio 0
	s_setprio 1
	v_mfma_f32_16x16x32_bf16 v[94:97], v[166:169], v[192:195], v[94:97]
	v_mfma_f32_16x16x32_bf16 v[90:93], v[184:187], v[192:195], v[90:93]
	v_mfma_f32_16x16x32_bf16 v[86:89], v[166:169], v[218:221], v[86:89]
	v_mfma_f32_16x16x32_bf16 v[82:85], v[184:187], v[218:221], v[82:85]
	v_mfma_f32_16x16x32_bf16 v[78:81], v[166:169], v[226:229], v[78:81]
	v_mfma_f32_16x16x32_bf16 v[74:77], v[184:187], v[226:229], v[74:77]
	v_mfma_f32_16x16x32_bf16 v[70:73], v[166:169], v[234:237], v[70:73]
	v_mfma_f32_16x16x32_bf16 v[66:69], v[184:187], v[234:237], v[66:69]
	v_mfma_f32_16x16x32_bf16 v[94:97], v[180:183], v[196:199], v[94:97]
	v_mfma_f32_16x16x32_bf16 v[90:93], v[188:191], v[196:199], v[90:93]
	v_mfma_f32_16x16x32_bf16 v[86:89], v[180:183], v[222:225], v[86:89]
	v_mfma_f32_16x16x32_bf16 v[82:85], v[188:191], v[222:225], v[82:85]
	v_mfma_f32_16x16x32_bf16 v[78:81], v[180:183], v[230:233], v[78:81]
	v_mfma_f32_16x16x32_bf16 v[74:77], v[188:191], v[230:233], v[74:77]
	v_mfma_f32_16x16x32_bf16 v[70:73], v[180:183], v[238:241], v[70:73]
	v_mfma_f32_16x16x32_bf16 v[66:69], v[188:191], v[238:241], v[66:69]
	s_setprio 0
	s_barrier
	s_mov_b32 m0, s33
	v_lshl_add_u64 v[208:209], v[246:247], 0, s[80:81]
	ds_read_b128 v[192:195], v200 offset:49152
	ds_read_b128 v[196:199], v200 offset:50176
	ds_read_b128 v[218:221], v200 offset:51200
	ds_read_b128 v[222:225], v200 offset:52224
	ds_read_b128 v[226:229], v200 offset:53248
	ds_read_b128 v[230:233], v200 offset:54272
	ds_read_b128 v[234:237], v200 offset:55296
	ds_read_b128 v[238:241], v200 offset:56320
	global_load_lds_dwordx4 v[208:209], off
	v_lshl_add_u64 v[208:209], v[248:249], 0, s[80:81]
	s_mov_b32 m0, s3
	v_lshl_add_u64 v[206:207], v[206:207], 0, s[80:81]
	global_load_lds_dwordx4 v[208:209], off
	v_lshl_add_u64 v[208:209], v[250:251], 0, s[80:81]
	s_mov_b32 m0, s47
	v_lshl_add_u64 v[204:205], v[204:205], 0, s[80:81]
	global_load_lds_dwordx4 v[208:209], off
	s_mov_b32 m0, s4
	v_lshl_add_u64 v[170:171], v[170:171], 0, s[80:81]
	global_load_lds_dwordx4 v[206:207], off
	s_mov_b32 m0, s55
	s_nop 0
	global_load_lds_dwordx4 v[204:205], off
	s_mov_b32 m0, s64
	s_nop 0
	global_load_lds_dwordx4 v[170:171], off
	s_waitcnt vmcnt(8)
	s_waitcnt lgkmcnt(0)
	s_barrier
	s_setprio 1
	s_waitcnt lgkmcnt(0)
	v_mfma_f32_16x16x32_bf16 v[62:65], v[150:153], v[192:195], v[62:65]
	v_mfma_f32_16x16x32_bf16 v[58:61], v[158:161], v[192:195], v[58:61]
	v_mfma_f32_16x16x32_bf16 v[54:57], v[150:153], v[218:221], v[54:57]
	v_mfma_f32_16x16x32_bf16 v[50:53], v[158:161], v[218:221], v[50:53]
	v_mfma_f32_16x16x32_bf16 v[46:49], v[150:153], v[226:229], v[46:49]
	v_mfma_f32_16x16x32_bf16 v[42:45], v[158:161], v[226:229], v[42:45]
	v_mfma_f32_16x16x32_bf16 v[38:41], v[150:153], v[234:237], v[38:41]
	v_mfma_f32_16x16x32_bf16 v[34:37], v[158:161], v[234:237], v[34:37]
	v_mfma_f32_16x16x32_bf16 v[62:65], v[154:157], v[196:199], v[62:65]
	v_mfma_f32_16x16x32_bf16 v[58:61], v[162:165], v[196:199], v[58:61]
	v_mfma_f32_16x16x32_bf16 v[54:57], v[154:157], v[222:225], v[54:57]
	v_mfma_f32_16x16x32_bf16 v[50:53], v[162:165], v[222:225], v[50:53]
	v_mfma_f32_16x16x32_bf16 v[46:49], v[154:157], v[230:233], v[46:49]
	v_mfma_f32_16x16x32_bf16 v[42:45], v[162:165], v[230:233], v[42:45]
	v_mfma_f32_16x16x32_bf16 v[38:41], v[154:157], v[238:241], v[38:41]
	v_mfma_f32_16x16x32_bf16 v[34:37], v[162:165], v[238:241], v[34:37]
	s_setprio 0
	s_setprio 1
	v_mfma_f32_16x16x32_bf16 v[30:33], v[166:169], v[192:195], v[30:33]
	v_mfma_f32_16x16x32_bf16 v[26:29], v[184:187], v[192:195], v[26:29]
	v_mfma_f32_16x16x32_bf16 v[22:25], v[166:169], v[218:221], v[22:25]
	s_add_u32 s38, s38, 0x100
	v_mfma_f32_16x16x32_bf16 v[18:21], v[184:187], v[218:221], v[18:21]
	s_addc_u32 s39, s39, 0
	v_mfma_f32_16x16x32_bf16 v[14:17], v[166:169], v[226:229], v[14:17]
	s_add_i32 s32, s62, 2
	v_mfma_f32_16x16x32_bf16 v[10:13], v[184:187], v[226:229], v[10:13]
	s_add_i32 s99, s62, -4
	v_mfma_f32_16x16x32_bf16 v[6:9], v[166:169], v[234:237], v[6:9]
	s_cmp_ge_i32 s99, s51
	v_mfma_f32_16x16x32_bf16 v[2:5], v[184:187], v[234:237], v[2:5]
	s_cselect_b32 s98, 0, 1
	v_mfma_f32_16x16x32_bf16 v[30:33], v[180:183], v[196:199], v[30:33]
	s_cmp_eq_u32 s94, s32
	v_mfma_f32_16x16x32_bf16 v[26:29], v[188:191], v[196:199], v[26:29]
	s_cselect_b64 vcc, -1, 0
	v_mfma_f32_16x16x32_bf16 v[22:25], v[180:183], v[222:225], v[22:25]
	s_and_b64 vcc, s[16:17], vcc
	v_mfma_f32_16x16x32_bf16 v[18:21], v[188:191], v[222:225], v[18:21]
	s_cselect_b32 s98, 0, s98
	v_mfma_f32_16x16x32_bf16 v[14:17], v[180:183], v[230:233], v[14:17]
	s_and_b64 vcc, exec, s[10:11]
	v_mfma_f32_16x16x32_bf16 v[10:13], v[188:191], v[230:233], v[10:13]
	s_cselect_b32 s98, s98, 0
	v_mfma_f32_16x16x32_bf16 v[6:9], v[180:183], v[238:241], v[6:9]
	s_cmp_lg_u32 s98, 0
	v_mfma_f32_16x16x32_bf16 v[2:5], v[188:191], v[238:241], v[2:5]
	s_setprio 0
	s_barrier
	s_cbranch_scc1 .Lk_fasta
	s_and_b64 vcc, exec, s[10:11]
	s_cbranch_vccnz .LBB0_2166
	s_waitcnt vmcnt(16)
	v_mov_b32_e32 v150, s50
	v_mov_b32_e32 v151, s5
	ds_read_b32 v150, v150
	ds_read_b32 v151, v151 offset:60
	s_mov_b64 s[40:41], 0
	s_waitcnt lgkmcnt(0)
	v_readfirstlane_b32 s10, v150
	v_readfirstlane_b32 s11, v151
	s_mul_i32 s11, s11, s18
	s_cmp_lt_u32 s10, s11
	s_cbranch_scc1 .LBB0_2166
	buffer_inv sc1
	s_mov_b64 s[40:41], -1
